# v44_swa3
# speedup vs baseline: 1.0041x; 1.0041x over previous
; DI float ex2(float x) { return __builtin_amdgcn_exp2f(x); }
; DI f32x16 zero16() { f32x16 z; for (int i = 0; i < 16; ++i) z[i] = 0.f; return z; }
; DI void swa_item(const Ctx& c, const float* sinks, int qt, int hq, int lane) {
;     const int r = lane & 31, h = lane >> 5, t0 = qt * 32, t = t0 + r, g = hq >> 2;
;     bf16x8 qf[4];
;     { const bf16* Qp = c.P + (size_t)t * PP + hq * 64 + 8 * h;
; #pragma unroll
;       for (int ks = 0; ks < 4; ++ks) qf[ks] = *(const bf16x8*)(Qp + 16 * ks); }
;     const float sc2 = 0.125f * LOG2E, slope2 = ex2(-(float)(hq + 1)) * LOG2E, sink2 = sinks[hq] * LOG2E;
;     float m = sink2, l = 0.f; f32x16 o[2] = {zero16(), zero16()};
;     const int kstart = t0 >= 128 ? t0 - 128 : 0;
.LBB0_1159:
	s_or_b64 exec, exec, s[8:9]
	v_readfirstlane_b32 s42, v0
	v_readlane_b32 s8, v244, 14
	s_cmp_ge_i32 s42, s8
	s_mov_b64 s[8:9], -1
	s_cbranch_scc1 .LBB0_1154
	v_readlane_b32 s8, v244, 13
	s_cmp_lt_i32 s42, s8
	s_cselect_b32 s8, s25, s24
	s_add_i32 s40, s42, s8
	s_cmpk_gt_i32 s40, 0x7ff
	s_mov_b64 s[8:9], -1
	s_cbranch_scc0 .LBB0_1164
	s_add_i32 s41, s40, 0xfffff800
	s_lshl_b32 s8, s41, 2
	s_and_b32 s9, s8, 0x7fffffe0
	s_and_b32 s43, s42, 7
	v_or_b32_e32 v0, s9, v151
	v_mov_b64_e32 v[2:3], s[26:27]
	v_mad_u64_u32 v[2:3], s[44:45], v0, s56, v[2:3]
	s_lshl_b32 s34, s43, 7
	v_lshl_add_u64 v[2:3], v[2:3], 0, s[34:35]
	v_lshl_add_u64 v[2:3], v[122:123], 1, v[2:3]
	s_add_i32 s34, s43, 1
	global_load_dwordx4 v[50:53], v[2:3], off
	global_load_dwordx4 v[54:57], v[2:3], off offset:32
	global_load_dwordx4 v[58:61], v[2:3], off offset:64
	global_load_dwordx4 v[62:65], v[2:3], off offset:96
	v_cvt_f32_ubyte0_e32 v2, s34
	v_exp_f32_e64 v2, -v2
	s_lshl_b32 s34, s43, 2
	s_lshl_b32 s8, s43, 6
	v_mov_b32_e32 v3, v1
	v_mul_f32_e32 v67, 0x3fb8aa3b, v2
	v_mov_b32_e32 v2, s34
	global_load_dword v2, v2, s[16:17]
	s_add_i32 s34, s9, 0xffffff80
	s_cmp_gt_u32 s41, 31
	s_cselect_b32 s41, s34, 0
	s_lshl_b32 s34, s42, 4
	s_and_b32 s34, s34, 64
	v_mov_b32_e32 v35, 0
	v_mov_b32_e32 v4, v35
	v_mov_b32_e32 v5, v35
	v_mov_b32_e32 v6, v35
	v_mov_b32_e32 v7, v35
	v_mov_b32_e32 v8, v35
	v_mov_b32_e32 v9, v35
	v_mov_b32_e32 v10, v35
	v_mov_b32_e32 v11, v35
	v_mov_b32_e32 v12, v35
	v_mov_b32_e32 v13, v35
	v_mov_b32_e32 v14, v35
	v_mov_b32_e32 v15, v35
	v_mov_b32_e32 v16, v35
	v_mov_b32_e32 v17, v35
	v_mov_b32_e32 v18, 0
	v_mov_b32_e32 v19, v35
	v_mov_b32_e32 v20, v35
	v_mov_b32_e32 v21, v35
	v_mov_b32_e32 v22, v35
	v_mov_b32_e32 v23, v35
	v_mov_b32_e32 v24, v35
	v_mov_b32_e32 v25, v35
	v_mov_b32_e32 v26, v35
	v_mov_b32_e32 v27, v35
	v_mov_b32_e32 v28, v35
	v_mov_b32_e32 v29, v35
	v_mov_b32_e32 v30, v35
	v_mov_b32_e32 v31, v35
	v_mov_b32_e32 v32, v35
	v_mov_b32_e32 v33, v35
	v_or_b32_e32 v228, s34, v151
	v_lshlrev_b32_e32 v228, 6, v228
	v_mov_b32_e32 v229, 0
	v_lshl_add_u64 v[68:69], v[126:127], 0, v[228:229]
	v_add_u32_e32 v228, s9, v152
	v_subrev_u32_e32 v71, s41, v228
	s_lshl_b32 s34, s34, 1
	v_add_u32_e32 v228, s41, v151
	v_mov_b64_e32 v[206:207], s[26:27]
	v_mad_i64_i32 v[206:207], vcc, v228, s56, v[206:207]
	v_lshl_add_u64 v[206:207], v[206:207], 0, s[34:35]
	v_lshl_add_u64 v[206:207], v[122:123], 1, v[206:207]
	v_lshl_add_u64 v[228:229], v[206:207], 0, s[68:69]
	v_add_co_u32_e32 v206, vcc, s0, v206
	global_load_dwordx4 v[240:243], v[228:229], off offset:32
	s_nop 0
	v_addc_co_u32_e32 v207, vcc, 0, v207, vcc
	global_load_dwordx4 v[224:227], v[206:207], off
	global_load_dwordx4 v[198:201], v[228:229], off offset:64
	global_load_dwordx4 v[202:205], v[228:229], off offset:96
	s_waitcnt vmcnt(4)
	v_mul_f32_e32 v70, 0x3fb8aa3b, v2
	s_nop 0
	v_mov_b32_e32 v34, v70
	v_mov_b32_e32 v2, 0
	v_mov_b32_e32 v3, v35
